# stack: + phase-2 sample-row scale/shift loads batched, tail-unit flag load issued one epilogue early
# baseline (speedup 1.0000x reference)
.LBB0_256:
	global_load_dwordx4 v[38:41], v[26:27], off
	global_load_dwordx4 v[42:45], v[26:27], off offset:1024
	global_load_dwordx4 v[16:19], v[26:27], off offset:3072
	global_load_dwordx4 v[20:23], v[26:27], off offset:2048
	v_ashrrev_i32_e32 v47, 2, v64
	v_add_u32_e32 v46, 0x4000, v64
	v_add_u32_e32 v48, 8, v47
	v_ashrrev_i32_e32 v47, 31, v46
	v_mad_i64_i32 v[48:49], s[0:1], v48, s3, v[28:29]
	v_lshlrev_b64 v[46:47], 11, v[46:47]
	v_lshl_add_u64 v[54:55], v[48:49], 0, s[48:49]
	v_lshl_add_u64 v[58:59], v[24:25], 0, v[46:47]
	v_lshl_add_u64 v[46:47], v[54:55], 0, v[66:67]
	v_lshl_add_u64 v[56:57], v[48:49], 0, v[66:67]
	global_load_dwordx4 v[46:49], v[46:47], off
	s_nop 0
	global_load_dwordx4 v[50:53], v[56:57], off
	v_lshl_add_u64 v[124:125], v[54:55], 0, v[68:69]
	global_load_dwordx4 v[100:103], v[124:125], off
	global_load_dwordx4 v[104:107], v[56:57], off offset:1024
	v_lshl_add_u64 v[126:127], v[54:55], 0, v[70:71]
	global_load_dwordx4 v[108:111], v[126:127], off
	global_load_dwordx4 v[112:115], v[56:57], off offset:2048
	v_lshl_add_u64 v[128:129], v[54:55], 0, v[72:73]
	global_load_dwordx4 v[116:119], v[128:129], off
	global_load_dwordx4 v[120:123], v[56:57], off offset:3072
	v_lshl_add_u64 v[60:61], v[54:55], 0, v[68:69]
	v_add_u32_e32 v64, s18, v64
	v_lshl_add_u64 v[26:27], v[26:27], 0, s[26:27]
	s_waitcnt vmcnt(0)
	v_pk_mul_f32 v[62:63], v[40:41], v[40:41]
	v_pk_mul_f32 v[74:75], v[38:39], v[38:39]
	s_waitcnt vmcnt(4)
	v_pk_mul_f32 v[76:77], v[44:45], v[44:45]
	v_pk_mul_f32 v[78:79], v[42:43], v[42:43]
	v_pk_mov_b32 v[84:85], v[74:75], v[62:63] op_sel:[1,0]
	v_mov_b32_e32 v75, v63
	v_pk_mov_b32 v[62:63], v[78:79], v[76:77] op_sel:[1,0]
	v_mov_b32_e32 v79, v77
	s_waitcnt vmcnt(3)
	v_mul_f32_e32 v83, v17, v17
	s_waitcnt vmcnt(2)
	v_mul_f32_e32 v80, v21, v21
	v_mul_f32_e32 v82, v23, v23
	v_pk_add_f32 v[74:75], v[84:85], v[74:75]
	v_pk_add_f32 v[62:63], v[62:63], v[78:79]
	v_mul_f32_e32 v65, v16, v16
	v_mul_f32_e32 v86, v18, v18
	v_mul_f32_e32 v87, v19, v19
	v_pk_fma_f32 v[76:77], v[20:21], v[20:21], v[80:81] op_sel_hi:[1,1,0]
	v_pk_fma_f32 v[80:81], v[22:23], v[22:23], v[82:83] op_sel_hi:[1,1,0]
	v_pk_add_f32 v[74:75], v[74:75], v[74:75] op_sel:[0,1] op_sel_hi:[1,0]
	v_pk_add_f32 v[62:63], v[62:63], v[62:63] op_sel:[0,1] op_sel_hi:[1,0]
	v_mov_b32_e32 v77, v86
	v_mov_b32_e32 v81, v87
	v_mov_b32_e32 v75, v65
	v_mov_b32_e32 v63, v83
	v_pk_add_f32 v[76:77], v[76:77], v[80:81]
	v_pk_add_f32 v[62:63], v[74:75], v[62:63]
	s_waitcnt vmcnt(1)
	v_pk_add_f32 v[46:47], v[46:47], 1.0 op_sel_hi:[1,0]
	v_pk_add_f32 v[62:63], v[62:63], v[76:77]
	v_pk_add_f32 v[48:49], v[48:49], 1.0 op_sel_hi:[1,0]
	v_add_f32_e32 v62, v62, v63
	s_nop 1
	v_add_f32_dpp v62, v62, v62 quad_perm:[1,0,3,2] row_mask:0xf bank_mask:0xf
	s_nop 1
	v_add_f32_dpp v62, v62, v62 quad_perm:[2,3,0,1] row_mask:0xf bank_mask:0xf
	s_nop 1
	v_add_f32_dpp v62, v62, v62 row_half_mirror row_mask:0xf bank_mask:0xf
	s_nop 1
	v_add_f32_dpp v62, v62, v62 row_ror:8 row_mask:0xf bank_mask:0xf
	v_mov_b32_e32 v63, v62
	s_nop 1
	v_permlane16_swap_b32_e32 v63, v62
	v_add_f32_e32 v62, v62, v63
	v_mov_b32_e32 v63, v62
	s_nop 1
	v_permlane32_swap_b32_e32 v63, v62
	v_add_f32_e32 v62, v62, v63
	v_fmamk_f32 v62, v62, 0x3a800000, v36
	v_mul_f32_e32 v63, 0x4f800000, v62
	v_cmp_gt_f32_e32 vcc, s6, v62
	s_nop 1
	v_cndmask_b32_e32 v62, v62, v63, vcc
	v_sqrt_f32_e32 v63, v62
	s_nop 0
	v_add_u32_e32 v65, -1, v63
	v_add_u32_e32 v74, 1, v63
	v_fma_f32 v75, -v65, v63, v62
	v_fma_f32 v76, -v74, v63, v62
	v_cmp_ge_f32_e64 s[0:1], 0, v75
	s_nop 1
	v_cndmask_b32_e64 v63, v63, v65, s[0:1]
	v_cmp_lt_f32_e64 s[0:1], 0, v76
	s_nop 1
	v_cndmask_b32_e64 v63, v63, v74, s[0:1]
	v_mul_f32_e32 v65, 0x37800000, v63
	v_cndmask_b32_e32 v63, v63, v65, vcc
	v_cmp_class_f32_e32 vcc, v62, v37
	s_nop 1
	v_cndmask_b32_e32 v62, v63, v62, vcc
	v_div_scale_f32 v63, s[0:1], v62, v62, 1.0
	v_rcp_f32_e32 v74, v63
	v_div_scale_f32 v65, vcc, 1.0, v62, 1.0
	v_fma_f32 v75, -v63, v74, 1.0
	v_fmac_f32_e32 v74, v75, v74
	v_mul_f32_e32 v75, v65, v74
	v_fma_f32 v76, -v63, v75, v65
	v_fmac_f32_e32 v75, v76, v74
	v_fma_f32 v63, -v63, v75, v65
	v_div_fmas_f32 v63, v63, v74, v75
	v_div_fixup_f32 v62, v63, v62, 1.0
	v_pk_mul_f32 v[38:39], v[38:39], v[62:63] op_sel_hi:[1,0]
	v_pk_mul_f32 v[40:41], v[40:41], v[62:63] op_sel_hi:[1,0]
	v_pk_mul_f32 v[38:39], v[0:1], v[38:39]
	v_pk_mul_f32 v[40:41], v[2:3], v[40:41]
	s_waitcnt vmcnt(0)
	v_pk_fma_f32 v[38:39], v[46:47], v[38:39], v[50:51]
	v_pk_fma_f32 v[40:41], v[48:49], v[40:41], v[52:53]
	v_cvt_pk_bf16_f32 v38, v38, v39
	v_pk_mul_f32 v[42:43], v[42:43], v[62:63] op_sel_hi:[1,0]
	v_cvt_pk_bf16_f32 v39, v40, v41
	global_store_dwordx2 v[58:59], v[38:39], off
	s_nop 1
	s_nop 0
	v_pk_mul_f32 v[44:45], v[44:45], v[62:63] op_sel_hi:[1,0]
	v_pk_mul_f32 v[42:43], v[4:5], v[42:43]
	v_pk_mul_f32 v[44:45], v[6:7], v[44:45]
	v_lshl_add_u64 v[50:51], v[54:55], 0, v[70:71]
	v_pk_mul_f32 v[20:21], v[20:21], v[62:63] op_sel_hi:[1,0]
	v_pk_mul_f32 v[22:23], v[22:23], v[62:63] op_sel_hi:[1,0]
	v_pk_mul_f32 v[20:21], v[8:9], v[20:21]
	v_pk_mul_f32 v[22:23], v[10:11], v[22:23]
	v_pk_mul_f32 v[16:17], v[16:17], v[62:63] op_sel_hi:[1,0]
	v_cmp_lt_i32_e32 vcc, s7, v64
	v_pk_mul_f32 v[18:19], v[18:19], v[62:63] op_sel_hi:[1,0]
	v_pk_mul_f32 v[16:17], v[12:13], v[16:17]
	s_or_b64 s[30:31], vcc, s[30:31]
	v_pk_mul_f32 v[18:19], v[14:15], v[18:19]
	v_pk_add_f32 v[38:39], v[100:101], 1.0 op_sel_hi:[1,0]
	v_pk_add_f32 v[40:41], v[102:103], 1.0 op_sel_hi:[1,0]
	v_pk_fma_f32 v[38:39], v[38:39], v[42:43], v[104:105]
	v_pk_fma_f32 v[40:41], v[40:41], v[44:45], v[106:107]
	v_cvt_pk_bf16_f32 v38, v38, v39
	v_lshl_add_u64 v[46:47], v[54:55], 0, v[72:73]
	v_cvt_pk_bf16_f32 v39, v40, v41
	global_store_dwordx2 v[58:59], v[38:39], off offset:512
	s_nop 1
	s_nop 0
	v_pk_add_f32 v[38:39], v[108:109], 1.0 op_sel_hi:[1,0]
	v_pk_add_f32 v[40:41], v[110:111], 1.0 op_sel_hi:[1,0]
	v_pk_fma_f32 v[20:21], v[38:39], v[20:21], v[112:113]
	v_pk_fma_f32 v[22:23], v[40:41], v[22:23], v[114:115]
	v_cvt_pk_bf16_f32 v20, v20, v21
	s_nop 0
	v_cvt_pk_bf16_f32 v21, v22, v23
	global_store_dwordx2 v[58:59], v[20:21], off offset:1024
	s_nop 1
	s_nop 0
	v_pk_add_f32 v[20:21], v[116:117], 1.0 op_sel_hi:[1,0]
	v_pk_add_f32 v[22:23], v[118:119], 1.0 op_sel_hi:[1,0]
	v_pk_fma_f32 v[16:17], v[16:17], v[20:21], v[120:121]
	v_pk_fma_f32 v[18:19], v[18:19], v[22:23], v[122:123]
	v_cvt_pk_bf16_f32 v16, v16, v17
	s_nop 0
	v_cvt_pk_bf16_f32 v17, v18, v19
	global_store_dwordx2 v[58:59], v[16:17], off offset:1536
	s_andn2_b64 exec, exec, s[30:31]
	s_cbranch_execnz .LBB0_256

.LBB0_331:
	s_cmp_lg_u32 s15, 5
	s_cbranch_scc1 .Lpf3_x
	s_cmp_lt_u32 s2, 172
	s_cbranch_scc1 .Lpf3_x
	s_cmp_gt_u32 s2, 251
	s_cbranch_scc1 .Lpf3_x
	v_mov_b32_e32 v253, 0x4a00
	global_load_dword v252, v253, s[94:95] sc1

.LBB0_403:
	s_cmp_lg_u32 s98, 1
	s_cbranch_scc1 .Ltl4_go
	s_mov_b32 s99, 0
	v_mov_b32_e32 v0, 0x4a00
	v_readfirstlane_b32 s3, v252
	s_nop 1
	s_cmp_ge_u32 s3, 44
	s_cbranch_scc1 .Ltl4_rdy

.LBB0_1226:
	s_cmp_lg_u32 s46, 5
	s_cbranch_scc1 .Lpf11_x
	s_cmp_lt_u32 s2, 172
	s_cbranch_scc1 .Lpf11_x
	s_cmp_gt_u32 s2, 251
	s_cbranch_scc1 .Lpf11_x
	v_mov_b32_e32 v253, 0x4a00
	global_load_dword v252, v253, s[94:95] sc1

.LBB0_1298:
	s_cmp_lg_u32 s98, 3
	s_cbranch_scc1 .Ltl12_go
	s_mov_b32 s99, 0
	v_mov_b32_e32 v0, 0x4a00
	v_readfirstlane_b32 s3, v252
	s_nop 1
	s_cmp_ge_u32 s3, 88
	s_cbranch_scc1 .Ltl12_rdy
